# hg_unit_c output stores write-through (sc1) to leave L2 clean at SEAM(4); first of two back-to-back grp_wait acquires removed
# baseline (speedup 1.0000x reference)
; __device__ __forceinline__ void grp_wait(unsigned* c, unsigned target) {
;     if (threadIdx.x == 0) {
;         unsigned sp = 0;
;         while (__hip_atomic_load(c, __ATOMIC_RELAXED, __HIP_MEMORY_SCOPE_AGENT) < target) { __builtin_amdgcn_s_sleep(2); if (++sp > (1u << 22)) break; }
;         __builtin_amdgcn_fence(__ATOMIC_ACQUIRE, "agent");
;         asm volatile("s_waitcnt vmcnt(0)" ::: "memory");
;     }
;     __syncthreads();
; }
; __global__ void __launch_bounds__(512, 2) mk_fwd(Args args) {
;     ...
;             grp_wait(cntA + 64 * (vb >> 5), 32u); grp_wait(cntA + 64 * ((vb >> 5) + 8), 32u);
.LBB0_263:
	global_load_dword v1, v0, s[8:9] sc1
	s_mov_b64 s[12:13], -1
	s_waitcnt vmcnt(0)
	v_cmp_lt_u32_e32 vcc, 31, v1
	s_cbranch_vccnz .LBB0_262
	s_sleep 2
	global_load_dword v1, v0, s[8:9] sc1
	s_waitcnt vmcnt(0)
	v_cmp_gt_u32_e32 vcc, 32, v1
	s_cbranch_vccz .LBB0_262
	s_sleep 2
	global_load_dword v1, v0, s[8:9] sc1
	s_waitcnt vmcnt(0)
	v_cmp_gt_u32_e32 vcc, 32, v1
	s_cbranch_vccz .LBB0_262
	s_sleep 2
	global_load_dword v1, v0, s[8:9] sc1
	s_waitcnt vmcnt(0)
	v_cmp_gt_u32_e32 vcc, 32, v1
	s_cbranch_vccz .LBB0_262
	s_sleep 2
	global_load_dword v1, v0, s[8:9] sc1
	s_waitcnt vmcnt(0)
	v_cmp_gt_u32_e32 vcc, 32, v1
	s_cbranch_vccz .LBB0_262
	s_add_i32 s1, s1, -5
	s_cmp_eq_u32 s1, 0
	s_cselect_b64 s[12:13], -1, 0
	s_sleep 2
	s_branch .LBB0_262
.LBB0_269:
	s_waitcnt vmcnt(0)
.LBB0_270:
	s_or_b64 exec, exec, s[10:11]
	s_barrier
	s_and_saveexec_b64 s[10:11], s[92:93]
	s_cbranch_execz .LBB0_280
	s_mov_b32 s1, 0x400001
	v_mov_b32_e32 v0, 0
	s_branch .LBB0_273

; #define LAS __attribute__((address_space(3)))
; __device__ __forceinline__ unsigned f2bf(float f) { unsigned u = __float_as_uint(f); return (u + 0x7fffu + ((u >> 16) & 1u)) >> 16; }
; __device__ __forceinline__ void hg_unit_c(LAS unsigned char* lds, int unit, const float* G, bf16_t* HQ, const bf16_t* HI, const float* ST, const float* ng) {
;     ...
;             for (int rg = 0; rg < 4; ++rg) {
;                 const int t = 16 * ti + 4 * g + rg, s = 16 * si + r;
;                 As[t * 72 + s] = (bf16_t)f2bf((s <= t) ? a[rg] : 0.f);
;             }
;         }
;         __syncthreads();
;         f32x4 o[4];
;         {
;             const bf16x8 vb0 = *(const LAS bf16x8*)(vT + (16 * w + r) * 72 + 8 * g), vb1 = *(const LAS bf16x8*)(vT + (16 * w + r) * 72 + 32 + 8 * g);
;             bf16x8 sb[4];
; #pragma unroll
;             for (int kk = 0; kk < 4; ++kk) sb[kk] = *(const LAS bf16x8*)(SpT + r * 136 + 32 * kk + 8 * g);
; #pragma unroll
;             for (int ti = 0; ti < 4; ++ti) {
;                 f32x4 a = (f32x4){0.f, 0.f, 0.f, 0.f};
;                 const bf16x8 a0 = *(const LAS bf16x8*)(As + (16 * ti + r) * 72 + 8 * g), a1 = *(const LAS bf16x8*)(As + (16 * ti + r) * 72 + 32 + 8 * g);
;                 a = __builtin_amdgcn_mfma_f32_16x16x32_bf16(a0, vb0, a, 0, 0, 0);
;                 a = __builtin_amdgcn_mfma_f32_16x16x32_bf16(a1, vb1, a, 0, 0, 0);
; #pragma unroll
;                 for (int kk = 0; kk < 4; ++kk) {
;                     const bf16x8 qf = *(const LAS bf16x8*)(qt + (16 * ti + r) * 136 + 32 * kk + 8 * g);
;                     a = __builtin_amdgcn_mfma_f32_16x16x32_bf16(qf, sb[kk], a, 0, 0, 0);
;                 }
;                 o[ti] = a;
;             }
;         }
;         hg_state_update(lds, S, w, r, g);
;         __syncthreads();
.LBB0_431:
	s_or_b64 exec, exec, s[40:41]
	s_nop 5
	v_cndmask_b32_e64 v32, v32, 0, s[18:19]
	v_bfe_u32 v36, v32, 16, 1
	v_add3_u32 v32, v32, v36, s90
	ds_write_b16_d16_hi v101, v32
	v_cndmask_b32_e64 v32, v33, 0, s[20:21]
	v_bfe_u32 v33, v32, 16, 1
	v_add3_u32 v32, v32, v33, s90
	ds_write_b16_d16_hi v102, v32
	v_cndmask_b32_e64 v32, v34, 0, s[22:23]
	v_bfe_u32 v33, v32, 16, 1
	v_add3_u32 v32, v32, v33, s90
	ds_write_b16_d16_hi v103, v32
	v_cndmask_b32_e64 v32, v35, 0, s[24:25]
	v_bfe_u32 v33, v32, 16, 1
	v_add3_u32 v32, v32, v33, s90
	ds_write_b16_d16_hi v104, v32
	s_waitcnt lgkmcnt(0)
	s_barrier
	ds_read_b128 v[168:171], v97
	ds_read_b128 v[36:39], v90 offset:53248
	ds_read_b128 v[172:175], v97 offset:64
	ds_read_b128 v[32:35], v90 offset:53312
	v_add_u32_e32 v80, v88, v85
	ds_read_b128 v[176:179], v80
	s_waitcnt lgkmcnt(3)
	v_mfma_f32_16x16x32_bf16 v[168:171], v[168:171], v[36:39], 0
	v_add_u32_e32 v81, v87, v86
	ds_read_b128 v[180:183], v81
	s_waitcnt lgkmcnt(2)
	v_mfma_f32_16x16x32_bf16 v[168:171], v[172:175], v[32:35], v[168:171]
	ds_read_b128 v[172:175], v80 offset:64
	ds_read_b128 v[184:187], v81 offset:64
	s_waitcnt lgkmcnt(2)
	v_mfma_f32_16x16x32_bf16 v[168:171], v[176:179], v[180:183], v[168:171]
	ds_read_b128 v[176:179], v80 offset:128
	ds_read_b128 v[188:191], v81 offset:128
	s_waitcnt lgkmcnt(2)
	v_mfma_f32_16x16x32_bf16 v[168:171], v[172:175], v[184:187], v[168:171]
	ds_read_b128 v[172:175], v80 offset:192
	ds_read_b128 v[192:195], v81 offset:192
	ds_read_b128 v[196:199], v129
	ds_read_b128 v[202:205], v129 offset:4352
	s_waitcnt lgkmcnt(4)
	v_mfma_f32_16x16x32_bf16 v[168:171], v[176:179], v[188:191], v[168:171]
	ds_read_b128 v[176:179], v98
	v_add_u32_e32 v80, 0x1cc00, v88
	s_waitcnt lgkmcnt(3)
	v_mfma_f32_16x16x32_bf16 v[168:171], v[172:175], v[192:195], v[168:171]
	ds_read_b128 v[172:175], v98 offset:64
	s_waitcnt lgkmcnt(1)
	v_mfma_f32_16x16x32_bf16 v[176:179], v[176:179], v[36:39], 0
	s_waitcnt lgkmcnt(0)
	v_mfma_f32_16x16x32_bf16 v[172:175], v[172:175], v[32:35], v[176:179]
	s_nop 5
	ds_read_b128 v[176:179], v129 offset:64
	v_mfma_f32_16x16x32_bf16 v[172:175], v[196:199], v[180:183], v[172:175]
	ds_read_b128 v[196:199], v129 offset:128
	s_waitcnt lgkmcnt(1)
	v_mfma_f32_16x16x32_bf16 v[172:175], v[176:179], v[184:187], v[172:175]
	ds_read_b128 v[176:179], v129 offset:192
	s_waitcnt lgkmcnt(1)
	v_mfma_f32_16x16x32_bf16 v[172:175], v[196:199], v[188:191], v[172:175]
	ds_read_b128 v[196:199], v99
	s_waitcnt lgkmcnt(1)
	v_mfma_f32_16x16x32_bf16 v[172:175], v[176:179], v[192:195], v[172:175]
	ds_read_b128 v[176:179], v99 offset:64
	s_waitcnt lgkmcnt(1)
	v_mfma_f32_16x16x32_bf16 v[196:199], v[196:199], v[36:39], 0
	s_waitcnt lgkmcnt(0)
	v_mfma_f32_16x16x32_bf16 v[176:179], v[176:179], v[32:35], v[196:199]
	s_nop 5
	ds_read_b128 v[196:199], v129 offset:4416
	v_mfma_f32_16x16x32_bf16 v[176:179], v[202:205], v[180:183], v[176:179]
	ds_read_b128 v[202:205], v129 offset:4480
	s_waitcnt lgkmcnt(1)
	v_mfma_f32_16x16x32_bf16 v[176:179], v[196:199], v[184:187], v[176:179]
	ds_read_b128 v[196:199], v129 offset:4544
	s_waitcnt lgkmcnt(1)
	v_mfma_f32_16x16x32_bf16 v[176:179], v[202:205], v[188:191], v[176:179]
	ds_read_b128 v[202:205], v100
	ds_read_b128 v[206:209], v100 offset:64
	s_waitcnt lgkmcnt(1)
	v_mfma_f32_16x16x32_bf16 v[202:205], v[202:205], v[36:39], 0
	v_mfma_f32_16x16x32_bf16 v[176:179], v[196:199], v[192:195], v[176:179]
	ds_read_b128 v[196:199], v129 offset:8704
	ds_read_b128 v[210:213], v129 offset:8768
	ds_read_b128 v[214:217], v80
	ds_read_b128 v[218:221], v129 offset:8832
	ds_read_b128 v[222:225], v129 offset:8896
	s_waitcnt lgkmcnt(2)
	v_pk_mul_f32 v[18:19], v[18:19], v[216:217]
	v_mfma_f32_16x16x32_bf16 v[202:205], v[206:209], v[32:35], v[202:205]
	ds_read_b128 v[206:209], v80 offset:64
	v_pk_mul_f32 v[16:17], v[16:17], v[214:215]
	s_waitcnt lgkmcnt(0)
	v_pk_mul_f32 v[26:27], v[26:27], v[208:209]
	v_mfma_f32_16x16x32_bf16 v[180:183], v[196:199], v[180:183], v[202:205]
	ds_read_b128 v[196:199], v91 offset:34816
	s_nop 1
	ds_read_b128 v[202:205], v91 offset:34880
	v_pk_mul_f32 v[24:25], v[24:25], v[206:207]
	v_mfma_f32_16x16x32_bf16 v[180:183], v[210:213], v[184:187], v[180:183]
	ds_read_b128 v[184:187], v80 offset:128
	ds_read_b128 v[206:209], v91 offset:37120
	ds_read_b128 v[210:213], v91 offset:37184
	s_waitcnt lgkmcnt(2)
	v_pk_mul_f32 v[22:23], v[22:23], v[186:187]
	v_mfma_f32_16x16x32_bf16 v[180:183], v[218:221], v[188:191], v[180:183]
	ds_read_b128 v[188:191], v80 offset:192
	v_pk_mul_f32 v[20:21], v[20:21], v[184:185]
	s_waitcnt lgkmcnt(0)
	v_pk_mul_f32 v[30:31], v[30:31], v[190:191]
	v_mfma_f32_16x16x32_bf16 v[16:19], v[196:199], v[36:39], v[16:19]
	v_mul_f32_e64 v28, v28, v188
	v_mul_f32_e64 v29, v29, v189
	v_mfma_f32_16x16x32_bf16 v[24:27], v[206:209], v[36:39], v[24:27]
	v_mfma_f32_16x16x32_bf16 v[180:183], v[222:225], v[192:195], v[180:183]
	ds_read_b128 v[184:187], v91 offset:39424
	ds_read_b128 v[192:195], v91 offset:39488
	ds_read_b128 v[188:191], v91 offset:41728
	ds_read_b128 v[196:199], v91 offset:41792
	ds_read_b128 v[214:217], v91 offset:44032
	ds_read_b128 v[218:221], v91 offset:44096
	v_mfma_f32_16x16x32_bf16 v[16:19], v[202:205], v[32:35], v[16:19]
	ds_read_b128 v[202:205], v80 offset:256
	ds_read_b128 v[222:225], v80 offset:320
	ds_read_b128 v[226:229], v91 offset:46336
	ds_read_b128 v[230:233], v91 offset:46400
	ds_read_b128 v[206:209], v91 offset:48640
	ds_read_b128 v[234:237], v91 offset:48704
	ds_read_b128 v[238:241], v80 offset:384
	ds_read_b128 v[242:245], v80 offset:448
	v_add_u32_e32 v80, 0x1e00, v131
	v_mfma_f32_16x16x32_bf16 v[24:27], v[210:213], v[32:35], v[24:27]
	ds_read_b128 v[210:213], v91 offset:50944
	ds_read_b128 v[246:249], v91 offset:51008
	s_waitcnt lgkmcnt(0)
	s_barrier
; #define LAS __attribute__((address_space(3)))
; __device__ __forceinline__ unsigned cvt_pk_bf16(float lo, float hi) { f32x2_t v = {lo, hi}; bf16x2_t b = __builtin_convertvector(v, bf16x2_t); return __builtin_bit_cast(unsigned, b); }
; __device__ __forceinline__ void hg_unit_c(LAS unsigned char* lds, int unit, const float* G, bf16_t* HQ, const bf16_t* HI, const float* ST, const float* ng) {
;     ...
;         __syncthreads();
; #pragma unroll
;         for (int ti = 0; ti < 4; ++ti)
; #pragma unroll
;             for (int rg = 0; rg < 4; ++rg) Os[(16 * ti + 4 * g + rg) * 132 + 16 * w + r] = o[ti][rg];
;         __syncthreads();
;         {
;             const int t = tid >> 3, sg = tid & 7;
;             f32x4 v[4]; float ss = 0.f;
; #pragma unroll
;             for (int i = 0; i < 4; ++i) { v[i] = *(const LAS f32x4*)(Os + t * 132 + 16 * sg + 4 * i); ss += (v[i][0] * v[i][0] + v[i][1] * v[i][1]) + (v[i][2] * v[i][2] + v[i][3] * v[i][3]); }
;             ss += __shfl_xor(ss, 1); ss += __shfl_xor(ss, 2); ss += __shfl_xor(ss, 4);
;             const float rstd = __builtin_amdgcn_rsqf(ss * (1.f / 128.f) + RMS_EPS);
;             const float* gp = ng + h * 128 + 16 * sg;
;             unsigned pk[8];
; #pragma unroll
;             for (int i = 0; i < 4; ++i) {
;                 const f32x4 gg = *(const f32x4*)(gp + 4 * i);
;                 pk[2 * i] = cvt_pk_bf16(v[i][0] * rstd * gg[0], v[i][1] * rstd * gg[1]);
;                 pk[2 * i + 1] = cvt_pk_bf16(v[i][2] * rstd * gg[2], v[i][3] * rstd * gg[3]);
;             }
;             bf16_t* op = HQ + (m0 + t) * 1024 + h * 128 + 16 * sg;
;             *(u32x4*)op = (u32x4){pk[0], pk[1], pk[2], pk[3]};
;             *(u32x4*)(op + 8) = (u32x4){pk[4], pk[5], pk[6], pk[7]};
;         }
	ds_write_b32 v130, v168
	ds_write2_b32 v131, v169, v170 offset1:132
	ds_write2_b32 v80, v172, v173 offset0:60 offset1:192
	v_add_u32_e32 v80, 0x2200, v131
	ds_write2_b32 v80, v174, v175 offset0:68 offset1:200
	v_add_u32_e32 v80, 0x3f00, v131
	ds_write2_b32 v80, v176, v177 offset0:60 offset1:192
	v_add_u32_e32 v80, 0x4400, v131
	ds_write2_b32 v80, v178, v179 offset0:4 offset1:136
	v_add_u32_e32 v80, 0x6000, v131
	ds_write2_b32 v80, v180, v181 offset0:60 offset1:192
	v_add_u32_e32 v80, 0x6400, v131
	ds_write_b32 v131, v171 offset:1056
	ds_write2_b32 v80, v182, v183 offset0:68 offset1:200
	s_waitcnt lgkmcnt(0)
	s_barrier
	global_load_dwordx4 v[168:171], v[56:57], off
	global_load_dwordx4 v[172:175], v[56:57], off offset:16
	global_load_dwordx4 v[176:179], v[56:57], off offset:32
	global_load_dwordx4 v[180:183], v[56:57], off offset:48
	v_mfma_f32_16x16x32_bf16 v[20:23], v[184:187], v[36:39], v[20:23]
	ds_read_b128 v[184:187], v132
	v_pk_mul_f32 v[0:1], v[0:1], v[202:203]
	v_pk_mul_f32 v[2:3], v[2:3], v[204:205]
	v_mfma_f32_16x16x32_bf16 v[28:31], v[188:191], v[36:39], v[28:31]
	v_mul_f32_e64 v6, v6, v224
	v_mul_f32_e64 v7, v7, v225
	s_waitcnt lgkmcnt(0)
	v_pk_mul_f32 v[80:81], v[186:187], v[186:187]
	v_pk_mul_f32 v[202:203], v[184:185], v[184:185]
	v_mfma_f32_16x16x32_bf16 v[20:23], v[192:195], v[32:35], v[20:23]
	v_pk_mov_b32 v[204:205], v[202:203], v[80:81] op_sel:[1,0]
	v_mov_b32_e32 v203, v81
	v_pk_add_f32 v[80:81], v[204:205], v[202:203]
	v_mfma_f32_16x16x32_bf16 v[28:31], v[196:199], v[32:35], v[28:31]
	ds_read_b128 v[188:191], v132 offset:16
	ds_read_b128 v[192:195], v132 offset:32
	ds_read_b128 v[196:199], v132 offset:48
	v_pk_add_f32 v[80:81], v[80:81], v[80:81] op_sel:[0,1] op_sel_hi:[1,0]
	v_pk_mul_f32 v[4:5], v[4:5], v[222:223]
	s_waitcnt lgkmcnt(2)
	v_pk_mul_f32 v[202:203], v[190:191], v[190:191]
	v_pk_mul_f32 v[204:205], v[188:189], v[188:189]
	v_mfma_f32_16x16x32_bf16 v[0:3], v[214:217], v[36:39], v[0:3]
	v_pk_mov_b32 v[214:215], v[204:205], v[202:203] op_sel:[1,0]
	v_mov_b32_e32 v205, v203
	v_pk_add_f32 v[202:203], v[214:215], v[204:205]
	s_waitcnt lgkmcnt(0)
	v_mul_f32_e32 v167, v196, v196
	v_mul_f32_e32 v201, v197, v197
	v_pk_add_f32 v[202:203], v[202:203], v[202:203] op_sel:[0,1] op_sel_hi:[1,0]
	v_mov_b32_e32 v81, v167
	v_mov_b32_e32 v203, v201
	v_pk_add_f32 v[80:81], v[80:81], v[202:203]
	v_mul_f32_e32 v202, v193, v193
	v_mul_f32_e32 v204, v198, v198
	v_pk_fma_f32 v[202:203], v[192:193], v[192:193], v[202:203] op_sel_hi:[1,1,0]
	v_mul_f32_e32 v214, v199, v199
	v_mov_b32_e32 v203, v204
	v_mul_f32_e32 v204, v195, v195
	v_pk_fma_f32 v[204:205], v[194:195], v[194:195], v[204:205] op_sel_hi:[1,1,0]
	v_pk_mul_f32 v[10:11], v[10:11], v[240:241]
	v_mov_b32_e32 v205, v214
	v_pk_add_f32 v[202:203], v[202:203], v[204:205]
	v_pk_mul_f32 v[8:9], v[8:9], v[238:239]
	v_pk_add_f32 v[80:81], v[80:81], v[202:203]
	v_pk_mul_f32 v[14:15], v[14:15], v[244:245]
	v_add_f32_e32 v80, v80, v81
	ds_bpermute_b32 v81, v92, v80
	v_pk_mul_f32 v[12:13], v[12:13], v[242:243]
	v_mfma_f32_16x16x32_bf16 v[4:7], v[226:229], v[36:39], v[4:7]
	s_waitcnt lgkmcnt(0)
	v_add_f32_e32 v80, v80, v81
	ds_bpermute_b32 v81, v93, v80
	v_mfma_f32_16x16x32_bf16 v[8:11], v[206:209], v[36:39], v[8:11]
	s_waitcnt lgkmcnt(0)
	v_add_f32_e32 v80, v80, v81
	ds_bpermute_b32 v81, v94, v80
	v_mfma_f32_16x16x32_bf16 v[12:15], v[210:213], v[36:39], v[12:15]
	s_waitcnt lgkmcnt(0)
	v_add_f32_e32 v36, v80, v81
	v_fmamk_f32 v36, v36, 0x3c000000, v133
	v_rsq_f32_e32 v80, v36
	v_mfma_f32_16x16x32_bf16 v[0:3], v[218:221], v[32:35], v[0:3]
	v_mul_f32_e64 v36, v190, v80
	v_mul_f32_e64 v37, v191, v80
	v_mfma_f32_16x16x32_bf16 v[4:7], v[230:233], v[32:35], v[4:7]
	v_mul_f32_e64 v38, v194, v80
	v_mul_f32_e64 v39, v195, v80
	s_waitcnt vmcnt(2)
	v_pk_mul_f32 v[36:37], v[174:175], v[36:37]
	v_mfma_f32_16x16x32_bf16 v[8:11], v[234:237], v[32:35], v[8:11]
	s_waitcnt vmcnt(1)
	v_pk_mul_f32 v[38:39], v[178:179], v[38:39]
	v_mfma_f32_16x16x32_bf16 v[12:15], v[246:249], v[32:35], v[12:15]
	v_mul_f32_e64 v32, v184, v80
	v_mul_f32_e64 v33, v185, v80
	v_pk_mul_f32 v[34:35], v[186:187], v[80:81] op_sel_hi:[1,0]
	v_pk_mul_f32 v[32:33], v[168:169], v[32:33]
	v_pk_mul_f32 v[34:35], v[170:171], v[34:35]
	v_cvt_pk_bf16_f32 v32, v32, v33
	v_cvt_pk_bf16_f32 v33, v34, v35
	v_pk_mul_f32 v[34:35], v[188:189], v[80:81] op_sel_hi:[1,0]
	s_nop 0
	v_pk_mul_f32 v[34:35], v[172:173], v[34:35]
	s_nop 0
	v_cvt_pk_bf16_f32 v34, v34, v35
	v_cvt_pk_bf16_f32 v35, v36, v37
	v_pk_mul_f32 v[36:37], v[192:193], v[80:81] op_sel_hi:[1,0]
	s_nop 0
	v_pk_mul_f32 v[36:37], v[176:177], v[36:37]
	s_nop 0
	v_cvt_pk_bf16_f32 v36, v36, v37
	v_cvt_pk_bf16_f32 v37, v38, v39
	v_pk_mul_f32 v[38:39], v[196:197], v[80:81] op_sel_hi:[1,0]
	v_pk_mul_f32 v[80:81], v[198:199], v[80:81] op_sel_hi:[1,0]
	s_waitcnt vmcnt(0)
	v_pk_mul_f32 v[38:39], v[180:181], v[38:39]
	v_pk_mul_f32 v[80:81], v[182:183], v[80:81]
	v_cvt_pk_bf16_f32 v38, v38, v39
	v_cvt_pk_bf16_f32 v39, v80, v81
	v_lshl_add_u64 v[80:81], v[58:59], 0, s[38:39]
	s_add_u32 s38, s38, 0x20000
	v_add_co_u32_e32 v80, vcc, s91, v80
	s_addc_u32 s39, s39, 0
	s_nop 0
	v_addc_co_u32_e32 v81, vcc, 0, v81, vcc
	s_cmp_lg_u32 s38, 0x80000
	global_store_dwordx4 v[80:81], v[32:35], off sc1
	global_store_dwordx4 v[80:81], v[36:39], off offset:16 sc1
	v_lshlrev_b32_e32 v43, 16, v43
	v_lshlrev_b32_e32 v76, 16, v76
	v_lshlrev_b32_e32 v78, 16, v78
	v_lshlrev_b32_e32 v80, 16, v64
	v_lshlrev_b32_e32 v64, 16, v45
	v_lshlrev_b32_e32 v45, 16, v66
	v_lshlrev_b32_e32 v66, 16, v47
	v_lshlrev_b32_e32 v47, 16, v68
	v_lshlrev_b32_e32 v68, 16, v67
	v_lshlrev_b32_e32 v67, 16, v72
	v_lshlrev_b32_e32 v72, 16, v71
	v_lshlrev_b32_e32 v71, 16, v65
	v_lshlrev_b32_e32 v65, 16, v70
	v_lshlrev_b32_e32 v70, 16, v69
	v_lshlrev_b32_e32 v69, 16, v74
	v_lshlrev_b32_e32 v74, 16, v73
	v_mov_b32_e32 v73, v80
	s_cbranch_scc0 .LBB0_429
